# strategy 4, other half: static s_setprio 1 for the older half (waves 0-3, the leading GEMM half), per-block flips deleted
# speedup vs baseline: 1.0040x; 1.0040x over previous
; #define LAS __attribute__((address_space(3)))
; __global__ void __launch_bounds__(512, 2) mk_fwd(Args a) {
;     extern __shared__ __attribute__((aligned(16))) unsigned char lds_raw[];
;     LAS unsigned char* lds = (LAS unsigned char*)lds_raw;
;     const int tid = threadIdx.x, lane = tid & 63, wid = __builtin_amdgcn_readfirstlane(tid >> 6);
;     const int G = gridDim.x, bid = blockIdx.x;
;     unsigned char* ws = a.ws;
_Z6mk_fwd4Args:
	s_load_dwordx2 s[84:85], s[0:1], 0xb0
	s_load_dwordx4 s[4:7], s[0:1], 0xa0
	s_load_dwordx4 s[88:91], s[0:1], 0xb8
	s_load_dword s86, s[0:1], 0xc8
	s_add_u32 s92, s0, 0xc8
	s_addc_u32 s93, s1, 0
	s_waitcnt lgkmcnt(0)
	v_writelane_b32 v254, s4, 0
	s_mov_b32 s87, s2
	s_add_u32 s2, s84, 0x30000
	v_writelane_b32 v254, s5, 1
	v_writelane_b32 v254, s6, 2
	v_writelane_b32 v254, s7, 3
	s_load_dwordx8 s[4:11], s[0:1], 0x80
	s_addc_u32 s3, s85, 0
	v_and_b32_e32 v1, 0x3ff, v0
	s_waitcnt lgkmcnt(0)
	v_writelane_b32 v254, s4, 4
	s_nop 1
	v_writelane_b32 v254, s5, 5
	v_writelane_b32 v254, s6, 6
	v_writelane_b32 v254, s7, 7
	v_writelane_b32 v254, s8, 8
	v_writelane_b32 v254, s9, 9
	v_writelane_b32 v254, s10, 10
	v_writelane_b32 v254, s11, 11
	v_writelane_b32 v254, s2, 12
	v_readfirstlane_b32 s64, v1
	s_nop 0
	v_writelane_b32 v254, s3, 13
	s_lshr_b32 s98, s64, 6
	s_cmp_ge_u32 s98, 4
	s_cbranch_scc1 .Lprio_done
	s_setprio 1
